# k39 + sample-row tiles no longer wait for the preceding epilogue's store drain (vmcnt(0) at their entry removed; barrier kept)
# speedup vs baseline: 1.0326x; 1.0010x over previous
; #define PG8_WAIT_V(n) asm volatile("s_waitcnt vmcnt(" #n ")" ::: "memory")
; #define PG8_BAR __builtin_amdgcn_s_barrier()
; template <class Epi, class Sched, bool ALIGN_EPI = false, bool SP2 = false>
; __device__ __forceinline__ void gemm_phase(PG8_LAS unsigned char* lds, const Gemm g, const Sched& S, const Epi& E) {
;     ...
;     PG8_WAIT_V(0);
;     if constexpr (!ALIGN_EPI) { if (wr == 0) PG8_BAR; }
;     PG8_BAR;
; template <class Elem>
; __device__ __forceinline__ void gemm_sample_rows(Frame& F, const bf16* A, const bf16* Bt, int K, const Elem& E) {
;     for (int st = blockIdx.x; st < 256; st += F.G) gemm_small64<Elem>(F.lds, A, Bt, K, MP + 64 * (st >> 4), 64 * (st & 15), E);
.LBB0_391:
	v_xor_b32_e32 v0, 1, v247
	v_cmp_lt_i32_e32 vcc, v0, v56
	s_nop 0
	s_lshl_b32 s3, s2, 6
	s_lshl_b32 s4, s30, 6
	v_cndmask_b32_e32 v0, v247, v0, vcc
	v_lshlrev_b32_e32 v42, 2, v0
	v_xor_b32_e32 v0, 2, v247
	v_cmp_lt_i32_e32 vcc, v0, v56
	s_lshl_b32 s5, s2, 2
	s_lshl_b32 s10, s30, 2
	v_cndmask_b32_e32 v0, v247, v0, vcc
	v_lshlrev_b32_e32 v43, 2, v0
	v_xor_b32_e32 v0, 4, v247
	v_cmp_lt_i32_e32 vcc, v0, v56
	s_movk_i32 s11, 0x1600
	v_mov_b64_e32 v[28:29], s[52:53]
	v_cndmask_b32_e32 v0, v247, v0, vcc
	v_lshlrev_b32_e32 v44, 2, v0
	v_mov_b32_e32 v31, 0
	s_mov_b32 s16, 0x16000
	s_mov_b32 s7, 0
	s_mov_b32 s17, 0x2c000
	s_mov_b32 s18, 0x42000
	s_movk_i32 s19, 0x110
	s_mov_b32 s20, s2
	s_barrier
	s_branch .LBB0_393

; #define PG8_WAIT_V(n) asm volatile("s_waitcnt vmcnt(" #n ")" ::: "memory")
; #define PG8_BAR __builtin_amdgcn_s_barrier()
; template <class Epi, class Sched, bool ALIGN_EPI = false, bool SP2 = false>
; __device__ __forceinline__ void gemm_phase(PG8_LAS unsigned char* lds, const Gemm g, const Sched& S, const Epi& E) {
;     ...
;     PG8_WAIT_V(0);
;     if constexpr (!ALIGN_EPI) { if (wr == 0) PG8_BAR; }
;     PG8_BAR;
; template <class Elem>
; __device__ __forceinline__ void gemm_sample_rows(Frame& F, const bf16* A, const bf16* Bt, int K, const Elem& E) {
;     for (int st = blockIdx.x; st < 256; st += F.G) gemm_small64<Elem>(F.lds, A, Bt, K, MP + 64 * (st >> 4), 64 * (st & 15), E);
.LBB0_943:
	v_xor_b32_e32 v0, 1, v246
	v_cmp_lt_i32_e32 vcc, v0, v112
	s_nop 0
	s_lshl_b32 s3, s2, 6
	s_lshl_b32 s4, s30, 6
	v_cndmask_b32_e32 v0, v246, v0, vcc
	v_lshlrev_b32_e32 v4, 2, v0
	v_xor_b32_e32 v0, 2, v246
	v_cmp_lt_i32_e32 vcc, v0, v112
	s_lshl_b32 s5, s2, 2
	s_lshl_b32 s8, s30, 2
	v_cndmask_b32_e32 v0, v246, v0, vcc
	v_lshlrev_b32_e32 v5, 2, v0
	v_xor_b32_e32 v0, 4, v246
	v_cmp_lt_i32_e32 vcc, v0, v112
	s_waitcnt lgkmcnt(0)
	v_mov_b32_e32 v1, 0
	s_mov_b32 s9, 0x8000
	v_cndmask_b32_e32 v0, v246, v0, vcc
	v_lshlrev_b32_e32 v6, 2, v0
	s_mov_b32 s1, 0
	s_mov_b32 s14, 0x10000
	s_mov_b32 s15, 0x18000
	s_movk_i32 s16, 0x110
	s_mov_b32 s17, s2
	s_barrier
	s_branch .LBB0_945

; #define PG8_WAIT_V(n) asm volatile("s_waitcnt vmcnt(" #n ")" ::: "memory")
; #define PG8_BAR __builtin_amdgcn_s_barrier()
; template <class Epi, class Sched, bool ALIGN_EPI = false, bool SP2 = false>
; __device__ __forceinline__ void gemm_phase(PG8_LAS unsigned char* lds, const Gemm g, const Sched& S, const Epi& E) {
;     ...
;     PG8_WAIT_V(0);
;     if constexpr (!ALIGN_EPI) { if (wr == 0) PG8_BAR; }
;     PG8_BAR;
; template <class Elem>
; __device__ __forceinline__ void gemm_sample_rows(Frame& F, const bf16* A, const bf16* Bt, int K, const Elem& E) {
;     for (int st = blockIdx.x; st < 256; st += F.G) gemm_small64<Elem>(F.lds, A, Bt, K, MP + 64 * (st >> 4), 64 * (st & 15), E);
.LBB0_1141:
	v_xor_b32_e32 v0, 1, v246
	v_cmp_lt_i32_e32 vcc, v0, v56
	s_nop 0
	s_lshl_b32 s3, s2, 6
	s_lshl_b32 s4, s30, 6
	v_cndmask_b32_e32 v0, v246, v0, vcc
	v_lshlrev_b32_e32 v42, 2, v0
	v_xor_b32_e32 v0, 2, v246
	v_cmp_lt_i32_e32 vcc, v0, v56
	s_lshl_b32 s5, s2, 2
	s_lshl_b32 s8, s30, 2
	v_cndmask_b32_e32 v0, v246, v0, vcc
	v_lshlrev_b32_e32 v43, 2, v0
	v_xor_b32_e32 v0, 4, v246
	v_cmp_lt_i32_e32 vcc, v0, v56
	s_movk_i32 s9, 0x1600
	v_mov_b64_e32 v[28:29], s[52:53]
	v_cndmask_b32_e32 v0, v246, v0, vcc
	v_lshlrev_b32_e32 v44, 2, v0
	v_mov_b32_e32 v31, 0
	s_mov_b32 s14, 0x16000
	s_mov_b32 s1, 0
	s_mov_b32 s15, 0x2c000
	s_mov_b32 s16, 0x42000
	s_movk_i32 s17, 0x110
	s_mov_b32 s18, s2
	s_barrier
	s_branch .LBB0_1143

; #define PG8_WAIT_V(n) asm volatile("s_waitcnt vmcnt(" #n ")" ::: "memory")
; #define PG8_BAR __builtin_amdgcn_s_barrier()
; template <class Epi, class Sched, bool ALIGN_EPI = false, bool SP2 = false>
; __device__ __forceinline__ void gemm_phase(PG8_LAS unsigned char* lds, const Gemm g, const Sched& S, const Epi& E) {
;     ...
;     PG8_WAIT_V(0);
;     if constexpr (!ALIGN_EPI) { if (wr == 0) PG8_BAR; }
;     PG8_BAR;
; template <class Elem>
; __device__ __forceinline__ void gemm_sample_rows(Frame& F, const bf16* A, const bf16* Bt, int K, const Elem& E) {
;     for (int st = blockIdx.x; st < 256; st += F.G) gemm_small64<Elem>(F.lds, A, Bt, K, MP + 64 * (st >> 4), 64 * (st & 15), E);
.LBB0_1259:
	s_nop 0
	s_lshl_b32 s0, s2, 6
	s_lshl_b32 s1, s30, 6
	s_lshl_b32 s3, s2, 2
	s_lshl_b32 s4, s30, 2
	v_mov_b32_e32 v93, 0
	s_mov_b32 s5, 0x8000
	s_mov_b32 s8, 0x10000
	s_mov_b32 s9, 0x18000
	s_movk_i32 s10, 0x110
	v_mov_b32_e32 v94, 0x358637bd
	s_barrier
